# level-1 scan outputs stored write-through: no L2 writeback before the completion counter
# speedup vs baseline: 1.0053x; 1.0053x over previous
.LBB0_665:
	v_readlane_b32 s2, v254, 27
	s_lshl_b32 s2, s2, 13
	v_mov_b32_e32 v181, 0
	v_lshl_add_u64 v[66:67], s[34:35], 0, v[180:181]
	s_ashr_i32 s3, s2, 31
	v_lshl_add_u64 v[66:67], v[66:67], 0, s[2:3]
	v_cvt_pk_bf16_f32 v18, v18, v19
	v_cvt_pk_bf16_f32 v19, v20, v21
	v_cvt_pk_bf16_f32 v20, v22, v23
	v_cvt_pk_bf16_f32 v21, v24, v25
	s_movk_i32 s2, 0x1000
	v_cvt_pk_bf16_f32 v22, v26, v27
	v_cvt_pk_bf16_f32 v23, v28, v29
	v_cvt_pk_bf16_f32 v24, v30, v31
	v_cvt_pk_bf16_f32 v25, v32, v33
	global_store_dwordx4 v[66:67], v[18:21], off sc1
	global_store_dwordx4 v[66:67], v[22:25], off offset:16 sc1
	v_add_co_u32_e32 v26, vcc, s2, v66
	v_cvt_pk_bf16_f32 v18, v34, v35
	v_cvt_pk_bf16_f32 v19, v36, v37
	v_cvt_pk_bf16_f32 v20, v38, v39
	v_cvt_pk_bf16_f32 v21, v40, v41
	v_cvt_pk_bf16_f32 v22, v42, v43
	v_cvt_pk_bf16_f32 v23, v44, v45
	v_cvt_pk_bf16_f32 v24, v46, v47
	v_cvt_pk_bf16_f32 v25, v48, v49
	global_store_dwordx4 v[66:67], v[18:21], off offset:2048 sc1
	global_store_dwordx4 v[66:67], v[22:25], off offset:2064 sc1
	v_addc_co_u32_e32 v27, vcc, 0, v67, vcc
	v_cvt_pk_bf16_f32 v18, v50, v51
	v_cvt_pk_bf16_f32 v19, v52, v53
	v_cvt_pk_bf16_f32 v20, v54, v55
	v_cvt_pk_bf16_f32 v21, v56, v57
	v_cvt_pk_bf16_f32 v2, v2, v3
	v_cvt_pk_bf16_f32 v3, v4, v5
	v_cvt_pk_bf16_f32 v4, v6, v7
	v_cvt_pk_bf16_f32 v5, v8, v9
	v_cvt_pk_bf16_f32 v22, v58, v59
	v_cvt_pk_bf16_f32 v23, v60, v61
	v_cvt_pk_bf16_f32 v24, v62, v63
	v_cvt_pk_bf16_f32 v25, v64, v65
	global_store_dwordx4 v[26:27], v[18:21], off sc1
	global_store_dwordx4 v[26:27], v[22:25], off offset:16 sc1
	v_cvt_pk_bf16_f32 v6, v10, v11
	v_cvt_pk_bf16_f32 v7, v12, v13
	v_cvt_pk_bf16_f32 v8, v14, v15
	v_cvt_pk_bf16_f32 v9, v16, v17
	global_store_dwordx4 v[26:27], v[2:5], off offset:2048 sc1
	global_store_dwordx4 v[26:27], v[6:9], off offset:2064 sc1

.LBB0_698:
	s_cmp_lg_u32 s37, 0
	s_cselect_b64 s[2:3], -1, 0
	v_writelane_b32 v254, s2, 42
	s_cmp_eq_u32 s37, 0
	s_waitcnt vmcnt(0)
	v_lshlrev_b32_e32 v130, 3, v186
	v_writelane_b32 v254, s3, 43
	s_cbranch_scc1 .LBB0_700
	v_readlane_b32 s6, v254, 27
	s_lshl_b32 s2, s6, 4
	s_and_b32 s2, s2, 0xfffffe0
	s_lshl_b32 s4, s6, 2
	v_or_b32_e32 v2, s2, v185
	s_movk_i32 s2, 0x110
	v_mul_lo_u32 v2, v2, s2
	s_add_u32 s2, s34, 0x8000
	s_addc_u32 s3, s35, 0
	s_lshl_b32 s5, s6, 7
	v_add_u32_e32 v12, s48, v2
	s_and_b32 s5, s5, 0x80
	v_add3_u32 v6, v12, s5, v130
	s_waitcnt lgkmcnt(0)
	s_barrier
	ds_read2_b64 v[2:5], v6 offset1:2
	ds_read2_b64 v[6:9], v6 offset0:4 offset1:6
	v_lshl_or_b32 v10, s6, 12, v178
	s_or_b32 s5, s4, 2
	v_ashrrev_i32_e32 v11, 31, v10
	s_lshl_b32 s6, s5, 5
	v_lshl_add_u64 v[10:11], s[2:3], 0, v[10:11]
	s_and_b32 s6, s6, 0xc0
	s_waitcnt lgkmcnt(1)
	global_store_dwordx4 v[10:11], v[2:5], off sc1
	s_waitcnt lgkmcnt(0)
	global_store_dwordx4 v[10:11], v[6:9], off offset:1024 sc1
	s_or_b32 s4, s4, 3
	v_add3_u32 v2, v12, s6, v130
	ds_read2_b64 v[2:5], v2 offset1:2
	v_lshl_or_b32 v6, s5, 10, v178
	s_lshl_b32 s5, s4, 5
	v_ashrrev_i32_e32 v7, 31, v6
	s_and_b32 s5, s5, 0xc0
	v_lshl_add_u64 v[10:11], s[2:3], 0, v[6:7]
	v_add3_u32 v6, v12, s5, v130
	ds_read2_b64 v[6:9], v6 offset0:4 offset1:6
	s_waitcnt lgkmcnt(1)
	global_store_dwordx4 v[10:11], v[2:5], off sc1
	s_nop 1
	v_lshl_or_b32 v2, s4, 10, v178
	v_ashrrev_i32_e32 v3, 31, v2
	v_lshl_add_u64 v[2:3], s[2:3], 0, v[2:3]
	s_waitcnt lgkmcnt(0)
	global_store_dwordx4 v[2:3], v[6:9], off sc1
.LBB0_700:
	s_waitcnt vmcnt(0)
	v_cmp_eq_u32_e32 vcc, 0, v0
	s_xor_b64 s[0:1], s[0:1], -1
	s_mov_b64 s[86:87], -1
	s_mov_b64 s[2:3], vcc
	s_mov_b32 s101, s0
	s_waitcnt lgkmcnt(0)
	s_barrier
	s_and_saveexec_b64 s[0:1], s[2:3]
	s_cbranch_execz .LBB0_703
	s_mov_b64 s[2:3], exec
	v_mbcnt_lo_u32_b32 v2, s2, 0
	s_waitcnt vmcnt(0)
	s_waitcnt vmcnt(0)
	v_mbcnt_hi_u32_b32 v2, s3, v2
	v_cmp_eq_u32_e32 vcc, 0, v2
	s_and_b64 s[4:5], exec, vcc
	s_mov_b64 exec, s[4:5]
	s_cbranch_execz .LBB0_703
	s_lshl_b32 s4, s47, 6
	s_ashr_i32 s5, s4, 31
	s_lshl_b64 s[4:5], s[4:5], 2
	s_add_u32 s4, s82, s4
	s_addc_u32 s5, s83, s5
	s_bcnt1_i32_b64 s2, s[2:3]
	s_mov_b32 s100, 0x19400
	s_cmp_lg_u32 s101, 0
	s_cselect_b32 s100, 0x18000, s100
	v_mov_b32_e32 v2, s100
	v_mov_b32_e32 v3, s2
	global_atomic_add v2, v3, s[4:5]
